# ple residual epilogue: bf16 x loads of the four row groups prefetched two groups ahead (same scheme as wout)
# baseline (speedup 1.0000x reference)
; template <bool XBF, bool WF32>
; DI void resid_epilogue(const float* __restrict__ xs, const bf16_t* __restrict__ xsb, float* __restrict__ out, bf16_t* __restrict__ xbn, float* __restrict__ ssq,
;                        const f32x4 (&acc)[2][2][4][2], int m0, int n0, int nt, bool wxb = true) {
;     ...
;     for (int bj = 0; bj < 2; ++bj)
; #pragma unroll
;         for (int nn = 0; nn < 2; ++nn) {
;             const size_t tok = (size_t)m0 + bj * 128 + wc * 32 + nn * 16 + fr;
;             float ss = 0.f;
; #pragma unroll
;             for (int ai = 0; ai < 2; ++ai) {
;                 float lo[8], hi[8];
;                 grp16(acc, ai, bj, nn, 1.f, lo, hi);
;                 const size_t o = tok * 1024 + n0 + ai * 128 + wr * 64 + 8 * fq;
;                 if (XBF) {
;                     const u32x4 xl = *(const u32x4*)(xsb + o), xh = *(const u32x4*)(xsb + o + 32);
; #pragma unroll
;                     for (int j = 0; j < 4; ++j) { lo[2 * j] += bf_lo(xl[j]); lo[2 * j + 1] += bf_hi(xl[j]); hi[2 * j] += bf_lo(xh[j]); hi[2 * j + 1] += bf_hi(xh[j]); }
;                 } else {
; #pragma unroll
;                     for (int q4 = 0; q4 < 2; ++q4) {
;                         const f32x4 xl = *(const f32x4*)(xs + o + 4 * q4), xh = *(const f32x4*)(xs + o + 32 + 4 * q4);
; #pragma unroll
;                         for (int j = 0; j < 4; ++j) { lo[4 * q4 + j] += xl[j]; hi[4 * q4 + j] += xh[j]; }
;                     }
;                 }
; #pragma unroll
;                 for (int i = 0; i < 8; ++i) ss += lo[i] * lo[i] + hi[i] * hi[i];
;                 if (WF32) {
; #pragma unroll
;                     for (int q4 = 0; q4 < 2; ++q4) {
;                         *(f32x4*)(out + o + 4 * q4) = (f32x4){lo[4 * q4], lo[4 * q4 + 1], lo[4 * q4 + 2], lo[4 * q4 + 3]};
; DI void ple_gate_apply(const Params& P, f32x4 (&acc)[2][2][4][2], int tile) {
; #pragma unroll
;     for (int ai = 0; ai < 2; ++ai)
; #pragma unroll
;         for (int bj = 0; bj < 2; ++bj)
; #pragma unroll
;             for (int nn = 0; nn < 2; ++nn) {
;                 const u32x4 gq = *ple_slot(P, tile, ai * 4 + bj * 2 + nn);
; #pragma unroll
;                 for (int e = 0; e < 8; ++e) {
;                     acc[ai][bj][e >> 2][nn][e & 3] *= dq8(gq[e >> 2], e & 3);
;                     acc[ai][bj][2 + (e >> 2)][nn][e & 3] *= dq8(gq[2 + (e >> 2)], e & 3);
;                 }
.LBB0_121:
	s_or_b64 exec, exec, s[54:55]
	v_mov_b32_e32 v18, v162
	s_nop 0
	v_ashrrev_i32_e32 v19, 31, v18
	v_lshl_add_u64 v[18:19], v[18:19], 4, s[8:9]
	global_load_dwordx4 v[158:161], v[18:19], off
	v_mov_b32_e32 v18, v162
	s_nop 0
	v_ashrrev_i32_e32 v19, 31, v18
	v_lshl_add_u64 v[18:19], v[18:19], 4, s[16:17]
	global_load_dwordx4 v[118:121], v[18:19], off
	v_mov_b32_e32 v18, v162
	s_nop 0
	v_ashrrev_i32_e32 v19, 31, v18
	v_lshl_add_u64 v[18:19], v[18:19], 4, s[20:21]
	global_load_dwordx4 v[78:81], v[18:19], off
	v_mov_b32_e32 v18, v162
	s_nop 0
	v_ashrrev_i32_e32 v19, 31, v18
	v_lshl_add_u64 v[18:19], v[18:19], 4, s[22:23]
	global_load_dwordx4 v[38:41], v[18:19], off
	v_mov_b32_e32 v18, v162
	s_nop 0
	v_ashrrev_i32_e32 v19, 31, v18
	v_lshl_add_u64 v[18:19], v[18:19], 4, s[24:25]
	global_load_dwordx4 v[154:157], v[18:19], off
	v_mov_b32_e32 v18, v162
	s_nop 0
	v_ashrrev_i32_e32 v19, 31, v18
	v_lshl_add_u64 v[18:19], v[18:19], 4, s[26:27]
	global_load_dwordx4 v[98:101], v[18:19], off
	v_mov_b32_e32 v18, v162
	s_nop 0
	v_ashrrev_i32_e32 v19, 31, v18
	v_lshl_add_u64 v[18:19], v[18:19], 4, s[28:29]
	global_load_dwordx4 v[58:61], v[18:19], off
	v_mov_b32_e32 v18, v162
	s_nop 0
	v_ashrrev_i32_e32 v19, 31, v18
	v_lshl_add_u64 v[18:19], v[18:19], 4, s[30:31]
	global_load_dwordx4 v[18:21], v[18:19], off
	v_mov_b32_e32 v0, v162
	s_waitcnt vmcnt(0)
	v_cvt_f32_ubyte1_e32 v173, v158
	v_ashrrev_i32_e32 v166, 8, v0
	v_and_b32_e32 v164, 15, v0
	v_bfe_u32 v185, v0, 4, 2
	v_lshrrev_b32_e32 v0, 1, v0
	v_and_b32_e32 v0, 0x60, v0
	v_or3_b32 v184, v164, v0, s82
	v_lshlrev_b32_e32 v164, 6, v166
	v_ashrrev_i32_e32 v165, 31, v164
	v_lshl_add_u64 v[164:165], v[164:165], 0, s[6:7]
	v_lshl_or_b32 v164, v185, 3, v164
	v_lshlrev_b32_e32 v0, 10, v184
	v_lshl_add_u64 v[170:171], v[0:1], 0, v[164:165]
	v_lshl_add_u64 v[168:169], v[170:171], 1, s[10:11]
	global_load_dwordx4 v[202:205], v[168:169], off
	global_load_dwordx4 v[206:209], v[168:169], off offset:64
	global_load_dwordx4 v[210:213], v[168:169], off offset:256
	global_load_dwordx4 v[214:217], v[168:169], off offset:320
	s_mov_b64 s[0:1], 0x8000
	v_lshl_add_u64 v[234:235], v[168:169], 0, s[0:1]
	s_mov_b64 s[0:1], 0x40000
	v_lshl_add_u64 v[236:237], v[168:169], 0, s[0:1]
	s_mov_b64 s[0:1], 0x48000
	v_lshl_add_u64 v[238:239], v[168:169], 0, s[0:1]
	global_load_dwordx4 v[218:221], v[234:235], off
	global_load_dwordx4 v[222:225], v[234:235], off offset:64
	global_load_dwordx4 v[226:229], v[234:235], off offset:256
	global_load_dwordx4 v[230:233], v[234:235], off offset:320
	s_waitcnt vmcnt(6)
	s_nop 1
	v_mov_b64_e32 v[186:187], v[202:203]
	v_mov_b64_e32 v[188:189], v[204:205]
	v_mov_b64_e32 v[190:191], v[206:207]
	v_mov_b64_e32 v[192:193], v[208:209]
	v_cvt_f32_ubyte0_e32 v172, v158
	v_pk_mul_f32 v[172:173], v[172:173], s[84:85] op_sel_hi:[1,0]
	v_cndmask_b32_e64 v0, 0, 1, s[14:15]
	v_cmp_ne_u32_e64 s[6:7], 1, v0
	s_andn2_b64 vcc, exec, s[14:15]
	v_lshlrev_b32_e32 v194, 16, v186
	v_and_b32_e32 v195, 0xffff0000, v186
	v_pk_fma_f32 v[122:123], v[122:123], v[172:173], v[194:195]
	v_cvt_f32_ubyte1_e32 v173, v160
	v_cvt_f32_ubyte0_e32 v172, v160
	v_pk_mul_f32 v[172:173], v[172:173], s[84:85] op_sel_hi:[1,0]
	v_lshlrev_b32_e32 v194, 16, v190
	v_and_b32_e32 v195, 0xffff0000, v190
	v_pk_fma_f32 v[126:127], v[126:127], v[172:173], v[194:195]
	v_cvt_f32_ubyte3_e32 v173, v158
	v_cvt_f32_ubyte2_e32 v172, v158
	v_pk_mul_f32 v[172:173], v[172:173], s[84:85] op_sel_hi:[1,0]
	v_lshlrev_b32_e32 v186, 16, v187
	v_and_b32_e32 v187, 0xffff0000, v187
	v_pk_fma_f32 v[124:125], v[124:125], v[172:173], v[186:187]
	v_cvt_f32_ubyte3_e32 v173, v160
	v_cvt_f32_ubyte2_e32 v172, v160
	v_pk_mul_f32 v[172:173], v[172:173], s[84:85] op_sel_hi:[1,0]
	v_lshlrev_b32_e32 v186, 16, v191
	v_and_b32_e32 v187, 0xffff0000, v191
	v_pk_fma_f32 v[128:129], v[128:129], v[172:173], v[186:187]
	v_cvt_f32_ubyte1_e32 v173, v159
	v_cvt_f32_ubyte0_e32 v172, v159
	v_pk_mul_f32 v[172:173], v[172:173], s[84:85] op_sel_hi:[1,0]
	v_lshlrev_b32_e32 v186, 16, v188
	v_and_b32_e32 v187, 0xffff0000, v188
	v_pk_fma_f32 v[130:131], v[130:131], v[172:173], v[186:187]
	v_cvt_f32_ubyte1_e32 v173, v161
	v_cvt_f32_ubyte0_e32 v172, v161
	v_pk_mul_f32 v[172:173], v[172:173], s[84:85] op_sel_hi:[1,0]
	v_lshlrev_b32_e32 v186, 16, v192
	v_and_b32_e32 v187, 0xffff0000, v192
	v_pk_fma_f32 v[134:135], v[134:135], v[172:173], v[186:187]
	v_cvt_f32_ubyte3_e32 v173, v159
	v_cvt_f32_ubyte2_e32 v172, v159
	v_pk_mul_f32 v[158:159], v[172:173], s[84:85] op_sel_hi:[1,0]
	v_lshlrev_b32_e32 v172, 16, v189
	v_and_b32_e32 v173, 0xffff0000, v189
	v_pk_fma_f32 v[132:133], v[132:133], v[158:159], v[172:173]
	v_cvt_f32_ubyte3_e32 v159, v161
	v_cvt_f32_ubyte2_e32 v158, v161
	v_pk_mul_f32 v[158:159], v[158:159], s[84:85] op_sel_hi:[1,0]
	v_lshlrev_b32_e32 v160, 16, v193
	v_and_b32_e32 v161, 0xffff0000, v193
	v_pk_fma_f32 v[136:137], v[136:137], v[158:159], v[160:161]
	v_lshl_add_u64 v[160:161], v[170:171], 2, s[60:61]
	v_lshl_add_u64 v[158:159], v[170:171], 1, s[12:13]
	global_store_dwordx4 v[160:161], v[122:125], off
	global_store_dwordx4 v[160:161], v[126:129], off offset:128
	global_store_dwordx4 v[160:161], v[130:133], off offset:16
	global_store_dwordx4 v[160:161], v[134:137], off offset:144
	s_cbranch_vccnz .LBB0_123
	v_cvt_pk_bf16_f32 v186, v122, v123
	v_cvt_pk_bf16_f32 v187, v124, v125
	v_cvt_pk_bf16_f32 v188, v130, v131
	v_cvt_pk_bf16_f32 v189, v132, v133
	global_store_dwordx4 v[158:159], v[186:189], off
	s_nop 1
	v_cvt_pk_bf16_f32 v186, v126, v127
	v_cvt_pk_bf16_f32 v187, v128, v129
	v_cvt_pk_bf16_f32 v188, v134, v135
	v_cvt_pk_bf16_f32 v189, v136, v137
	global_store_dwordx4 v[158:159], v[186:189], off offset:64
; template <bool XBF, bool WF32>
; DI void resid_epilogue(const float* __restrict__ xs, const bf16_t* __restrict__ xsb, float* __restrict__ out, bf16_t* __restrict__ xbn, float* __restrict__ ssq,
;                        const f32x4 (&acc)[2][2][4][2], int m0, int n0, int nt, bool wxb = true) {
;     ...
;     for (int bj = 0; bj < 2; ++bj)
; #pragma unroll
;         for (int nn = 0; nn < 2; ++nn) {
;             const size_t tok = (size_t)m0 + bj * 128 + wc * 32 + nn * 16 + fr;
;             float ss = 0.f;
; #pragma unroll
;             for (int ai = 0; ai < 2; ++ai) {
;                 float lo[8], hi[8];
;                 grp16(acc, ai, bj, nn, 1.f, lo, hi);
;                 const size_t o = tok * 1024 + n0 + ai * 128 + wr * 64 + 8 * fq;
;                 if (XBF) {
;                     const u32x4 xl = *(const u32x4*)(xsb + o), xh = *(const u32x4*)(xsb + o + 32);
; #pragma unroll
;                     for (int j = 0; j < 4; ++j) { lo[2 * j] += bf_lo(xl[j]); lo[2 * j + 1] += bf_hi(xl[j]); hi[2 * j] += bf_lo(xh[j]); hi[2 * j + 1] += bf_hi(xh[j]); }
;                 } else {
; #pragma unroll
;                     for (int q4 = 0; q4 < 2; ++q4) {
;                         const f32x4 xl = *(const f32x4*)(xs + o + 4 * q4), xh = *(const f32x4*)(xs + o + 32 + 4 * q4);
; #pragma unroll
;                         for (int j = 0; j < 4; ++j) { lo[4 * q4 + j] += xl[j]; hi[4 * q4 + j] += xh[j]; }
;                     }
;                 }
; #pragma unroll
;                 for (int i = 0; i < 8; ++i) ss += lo[i] * lo[i] + hi[i] * hi[i];
;                 if (WF32) {
; #pragma unroll
;                     for (int q4 = 0; q4 < 2; ++q4) {
;                         *(f32x4*)(out + o + 4 * q4) = (f32x4){lo[4 * q4], lo[4 * q4 + 1], lo[4 * q4 + 2], lo[4 * q4 + 3]};
;                         *(f32x4*)(out + o + 32 + 4 * q4) = (f32x4){hi[4 * q4], hi[4 * q4 + 1], hi[4 * q4 + 2], hi[4 * q4 + 3]};
;                     }
;                 }
; DI void ple_gate_apply(const Params& P, f32x4 (&acc)[2][2][4][2], int tile) {
;     ...
;                 const u32x4 gq = *ple_slot(P, tile, ai * 4 + bj * 2 + nn);
; #pragma unroll
;                 for (int e = 0; e < 8; ++e) {
;                     acc[ai][bj][e >> 2][nn][e & 3] *= dq8(gq[e >> 2], e & 3);
;                     acc[ai][bj][2 + (e >> 2)][nn][e & 3] *= dq8(gq[2 + (e >> 2)], e & 3);
;                 }
.LBB0_123:
	v_cvt_f32_ubyte1_e32 v171, v154
	v_cvt_f32_ubyte0_e32 v170, v154
	v_pk_mul_f32 v[172:173], v[170:171], s[84:85] op_sel_hi:[1,0]
	v_cvt_f32_ubyte1_e32 v171, v156
	v_cvt_f32_ubyte0_e32 v170, v156
	v_pk_mul_f32 v[186:187], v[170:171], s[84:85] op_sel_hi:[1,0]
	v_cvt_f32_ubyte3_e32 v171, v154
	v_cvt_f32_ubyte2_e32 v170, v154
	v_pk_mul_f32 v[188:189], v[170:171], s[84:85] op_sel_hi:[1,0]
	v_cvt_f32_ubyte3_e32 v171, v156
	v_cvt_f32_ubyte2_e32 v170, v156
	v_pk_mul_f32 v[190:191], v[170:171], s[84:85] op_sel_hi:[1,0]
	v_cvt_f32_ubyte1_e32 v171, v155
	v_cvt_f32_ubyte0_e32 v170, v155
	v_pk_mul_f32 v[192:193], v[170:171], s[84:85] op_sel_hi:[1,0]
	v_cvt_f32_ubyte1_e32 v171, v157
	v_cvt_f32_ubyte0_e32 v170, v157
	v_pk_mul_f32 v[194:195], v[170:171], s[84:85] op_sel_hi:[1,0]
	v_cvt_f32_ubyte3_e32 v171, v155
	v_cvt_f32_ubyte2_e32 v170, v155
	v_cvt_f32_ubyte3_e32 v155, v157
	v_cvt_f32_ubyte2_e32 v154, v157
	v_pk_mul_f32 v[196:197], v[170:171], s[84:85] op_sel_hi:[1,0]
	v_pk_mul_f32 v[198:199], v[154:155], s[84:85] op_sel_hi:[1,0]
	s_waitcnt vmcnt(8)
	s_nop 1
	v_mov_b64_e32 v[154:155], v[210:211]
	v_mov_b64_e32 v[156:157], v[212:213]
	v_mov_b64_e32 v[168:169], v[214:215]
	v_mov_b64_e32 v[170:171], v[216:217]
	global_load_dwordx4 v[202:205], v[236:237], off
	global_load_dwordx4 v[206:209], v[236:237], off offset:64
	global_load_dwordx4 v[210:213], v[236:237], off offset:256
	global_load_dwordx4 v[214:217], v[236:237], off offset:320
	s_and_b64 vcc, exec, s[6:7]
	v_lshlrev_b32_e32 v200, 16, v154
	v_and_b32_e32 v201, 0xffff0000, v154
	v_lshlrev_b32_e32 v154, 16, v155
	v_and_b32_e32 v155, 0xffff0000, v155
	v_pk_fma_f32 v[148:149], v[148:149], v[188:189], v[154:155]
	v_lshlrev_b32_e32 v154, 16, v169
	v_and_b32_e32 v155, 0xffff0000, v169
	v_pk_fma_f32 v[152:153], v[152:153], v[190:191], v[154:155]
	v_lshlrev_b32_e32 v154, 16, v156
	v_and_b32_e32 v155, 0xffff0000, v156
	v_pk_fma_f32 v[138:139], v[138:139], v[192:193], v[154:155]
	v_lshlrev_b32_e32 v154, 16, v170
	v_and_b32_e32 v155, 0xffff0000, v170
	v_pk_fma_f32 v[142:143], v[142:143], v[194:195], v[154:155]
	v_lshlrev_b32_e32 v154, 16, v157
	v_and_b32_e32 v155, 0xffff0000, v157
	v_pk_fma_f32 v[146:147], v[146:147], v[172:173], v[200:201]
	v_lshlrev_b32_e32 v172, 16, v168
	v_and_b32_e32 v173, 0xffff0000, v168
	v_pk_fma_f32 v[140:141], v[140:141], v[196:197], v[154:155]
	v_lshlrev_b32_e32 v154, 16, v171
	v_and_b32_e32 v155, 0xffff0000, v171
	v_pk_fma_f32 v[150:151], v[150:151], v[186:187], v[172:173]
	v_pk_fma_f32 v[144:145], v[144:145], v[198:199], v[154:155]
	global_store_dwordx4 v[160:161], v[146:149], off offset:512
	global_store_dwordx4 v[160:161], v[150:153], off offset:640
	global_store_dwordx4 v[160:161], v[138:141], off offset:528
	global_store_dwordx4 v[160:161], v[142:145], off offset:656
	s_cbranch_vccnz .LBB0_125
	v_cvt_pk_bf16_f32 v154, v146, v147
	v_cvt_pk_bf16_f32 v155, v148, v149
	v_cvt_pk_bf16_f32 v156, v138, v139
	v_cvt_pk_bf16_f32 v157, v140, v141
	global_store_dwordx4 v[158:159], v[154:157], off offset:256
	s_nop 1
	v_cvt_pk_bf16_f32 v154, v150, v151
	v_cvt_pk_bf16_f32 v155, v152, v153
	v_cvt_pk_bf16_f32 v156, v142, v143
	v_cvt_pk_bf16_f32 v157, v144, v145
	global_store_dwordx4 v[158:159], v[154:157], off offset:320

; template <bool XBF, bool WF32>
; DI void resid_epilogue(const float* __restrict__ xs, const bf16_t* __restrict__ xsb, float* __restrict__ out, bf16_t* __restrict__ xbn, float* __restrict__ ssq,
;                        const f32x4 (&acc)[2][2][4][2], int m0, int n0, int nt, bool wxb = true) {
;     ...
;     for (int bj = 0; bj < 2; ++bj)
; #pragma unroll
;         for (int nn = 0; nn < 2; ++nn) {
;             const size_t tok = (size_t)m0 + bj * 128 + wc * 32 + nn * 16 + fr;
;             float ss = 0.f;
; #pragma unroll
;             for (int ai = 0; ai < 2; ++ai) {
;                 float lo[8], hi[8];
;                 grp16(acc, ai, bj, nn, 1.f, lo, hi);
;                 const size_t o = tok * 1024 + n0 + ai * 128 + wr * 64 + 8 * fq;
;                 if (XBF) {
;                     const u32x4 xl = *(const u32x4*)(xsb + o), xh = *(const u32x4*)(xsb + o + 32);
; #pragma unroll
;                     for (int j = 0; j < 4; ++j) { lo[2 * j] += bf_lo(xl[j]); lo[2 * j + 1] += bf_hi(xl[j]); hi[2 * j] += bf_lo(xh[j]); hi[2 * j + 1] += bf_hi(xh[j]); }
;                 } else {
; #pragma unroll
;                     for (int q4 = 0; q4 < 2; ++q4) {
;                         const f32x4 xl = *(const f32x4*)(xs + o + 4 * q4), xh = *(const f32x4*)(xs + o + 32 + 4 * q4);
; #pragma unroll
;                         for (int j = 0; j < 4; ++j) { lo[4 * q4 + j] += xl[j]; hi[4 * q4 + j] += xh[j]; }
;                     }
;                 }
; #pragma unroll
;                 for (int i = 0; i < 8; ++i) ss += lo[i] * lo[i] + hi[i] * hi[i];
;                 if (WF32) {
; #pragma unroll
;                     for (int q4 = 0; q4 < 2; ++q4) {
;                         *(f32x4*)(out + o + 4 * q4) = (f32x4){lo[4 * q4], lo[4 * q4 + 1], lo[4 * q4 + 2], lo[4 * q4 + 3]};
;                         *(f32x4*)(out + o + 32 + 4 * q4) = (f32x4){hi[4 * q4], hi[4 * q4 + 1], hi[4 * q4 + 2], hi[4 * q4 + 3]};
;                     }
;                 }
; DI void ple_gate_apply(const Params& P, f32x4 (&acc)[2][2][4][2], int tile) {
;     ...
;                 const u32x4 gq = *ple_slot(P, tile, ai * 4 + bj * 2 + nn);
; #pragma unroll
;                 for (int e = 0; e < 8; ++e) {
;                     acc[ai][bj][e >> 2][nn][e & 3] *= dq8(gq[e >> 2], e & 3);
;                     acc[ai][bj][2 + (e >> 2)][nn][e & 3] *= dq8(gq[2 + (e >> 2)], e & 3);
;                 }
.LBB0_127:
	s_or_b64 exec, exec, s[20:21]
	s_waitcnt lgkmcnt(0)
	v_cvt_f32_ubyte1_e32 v125, v118
	v_cvt_f32_ubyte0_e32 v124, v118
	v_pk_mul_f32 v[138:139], v[124:125], s[84:85] op_sel_hi:[1,0]
	v_cvt_f32_ubyte1_e32 v125, v120
	v_cvt_f32_ubyte0_e32 v124, v120
	v_pk_mul_f32 v[140:141], v[124:125], s[84:85] op_sel_hi:[1,0]
	v_cvt_f32_ubyte3_e32 v125, v118
	v_cvt_f32_ubyte2_e32 v124, v118
	v_pk_mul_f32 v[142:143], v[124:125], s[84:85] op_sel_hi:[1,0]
	v_cvt_f32_ubyte3_e32 v125, v120
	v_cvt_f32_ubyte2_e32 v124, v120
	v_pk_mul_f32 v[144:145], v[124:125], s[84:85] op_sel_hi:[1,0]
	v_cvt_f32_ubyte1_e32 v125, v119
	v_cvt_f32_ubyte0_e32 v124, v119
	v_pk_mul_f32 v[146:147], v[124:125], s[84:85] op_sel_hi:[1,0]
	v_cvt_f32_ubyte1_e32 v125, v121
	v_cvt_f32_ubyte0_e32 v124, v121
	v_pk_mul_f32 v[148:149], v[124:125], s[84:85] op_sel_hi:[1,0]
	v_cvt_f32_ubyte3_e32 v125, v119
	v_cvt_f32_ubyte2_e32 v124, v119
	v_cvt_f32_ubyte3_e32 v119, v121
	v_cvt_f32_ubyte2_e32 v118, v121
	v_pk_mul_f32 v[120:121], v[118:119], s[84:85] op_sel_hi:[1,0]
	v_pk_mul_f32 v[150:151], v[124:125], s[84:85] op_sel_hi:[1,0]
	v_or_b32_e32 v128, 16, v184
	v_lshlrev_b32_e32 v0, 10, v128
	v_lshl_add_u64 v[118:119], v[0:1], 0, v[164:165]
	v_lshl_add_u64 v[124:125], v[118:119], 1, s[10:11]
	s_waitcnt vmcnt(14)
	s_nop 1
	v_mov_b64_e32 v[130:131], v[218:219]
	v_mov_b64_e32 v[132:133], v[220:221]
	v_mov_b64_e32 v[134:135], v[222:223]
	v_mov_b64_e32 v[136:137], v[224:225]
	s_and_b64 vcc, exec, s[6:7]
	v_lshlrev_b32_e32 v152, 16, v130
	v_and_b32_e32 v153, 0xffff0000, v130
	v_lshlrev_b32_e32 v130, 16, v131
	v_and_b32_e32 v131, 0xffff0000, v131
	v_pk_fma_f32 v[112:113], v[112:113], v[142:143], v[130:131]
	v_lshlrev_b32_e32 v130, 16, v135
	v_and_b32_e32 v131, 0xffff0000, v135
	v_pk_fma_f32 v[116:117], v[116:117], v[144:145], v[130:131]
	v_lshlrev_b32_e32 v130, 16, v132
	v_and_b32_e32 v131, 0xffff0000, v132
	v_pk_fma_f32 v[102:103], v[102:103], v[146:147], v[130:131]
	v_lshlrev_b32_e32 v130, 16, v136
	v_and_b32_e32 v131, 0xffff0000, v136
	v_pk_fma_f32 v[106:107], v[106:107], v[148:149], v[130:131]
	v_lshlrev_b32_e32 v130, 16, v133
	v_and_b32_e32 v131, 0xffff0000, v133
	v_pk_fma_f32 v[110:111], v[110:111], v[138:139], v[152:153]
	v_lshlrev_b32_e32 v138, 16, v134
	v_and_b32_e32 v139, 0xffff0000, v134
	v_pk_fma_f32 v[104:105], v[104:105], v[150:151], v[130:131]
	v_lshlrev_b32_e32 v130, 16, v137
	v_and_b32_e32 v131, 0xffff0000, v137
	v_pk_fma_f32 v[114:115], v[114:115], v[140:141], v[138:139]
	v_pk_fma_f32 v[108:109], v[108:109], v[120:121], v[130:131]
	v_lshl_add_u64 v[120:121], v[118:119], 2, s[60:61]
	v_lshl_add_u64 v[118:119], v[118:119], 1, s[12:13]
	global_store_dwordx4 v[120:121], v[110:113], off
	global_store_dwordx4 v[120:121], v[114:117], off offset:128
	global_store_dwordx4 v[120:121], v[102:105], off offset:16
	global_store_dwordx4 v[120:121], v[106:109], off offset:144
	s_cbranch_vccnz .LBB0_129
	v_cvt_pk_bf16_f32 v130, v110, v111
	v_cvt_pk_bf16_f32 v131, v112, v113
	v_cvt_pk_bf16_f32 v132, v102, v103
	v_cvt_pk_bf16_f32 v133, v104, v105
	global_store_dwordx4 v[118:119], v[130:133], off
	s_nop 1
	v_cvt_pk_bf16_f32 v130, v114, v115
	v_cvt_pk_bf16_f32 v131, v116, v117
	v_cvt_pk_bf16_f32 v132, v106, v107
	v_cvt_pk_bf16_f32 v133, v108, v109
	global_store_dwordx4 v[118:119], v[130:133], off offset:64
.LBB0_129:
	s_nop 1
	v_cvt_f32_ubyte1_e32 v131, v98
	v_cvt_f32_ubyte0_e32 v130, v98
	v_pk_mul_f32 v[134:135], v[130:131], s[84:85] op_sel_hi:[1,0]
	v_cvt_f32_ubyte1_e32 v131, v100
	v_cvt_f32_ubyte0_e32 v130, v100
	v_pk_mul_f32 v[136:137], v[130:131], s[84:85] op_sel_hi:[1,0]
	v_cvt_f32_ubyte3_e32 v131, v98
	v_cvt_f32_ubyte2_e32 v130, v98
	v_pk_mul_f32 v[138:139], v[130:131], s[84:85] op_sel_hi:[1,0]
	v_cvt_f32_ubyte3_e32 v131, v100
	v_cvt_f32_ubyte2_e32 v130, v100
	v_pk_mul_f32 v[140:141], v[130:131], s[84:85] op_sel_hi:[1,0]
	v_cvt_f32_ubyte1_e32 v131, v99
	v_cvt_f32_ubyte0_e32 v130, v99
	v_pk_mul_f32 v[142:143], v[130:131], s[84:85] op_sel_hi:[1,0]
	v_cvt_f32_ubyte1_e32 v131, v101
	v_cvt_f32_ubyte0_e32 v130, v101
	v_pk_mul_f32 v[144:145], v[130:131], s[84:85] op_sel_hi:[1,0]
	v_cvt_f32_ubyte3_e32 v131, v99
	v_cvt_f32_ubyte2_e32 v130, v99
	v_cvt_f32_ubyte3_e32 v99, v101
	v_cvt_f32_ubyte2_e32 v98, v101
	v_pk_mul_f32 v[146:147], v[130:131], s[84:85] op_sel_hi:[1,0]
	v_pk_mul_f32 v[148:149], v[98:99], s[84:85] op_sel_hi:[1,0]
	s_waitcnt vmcnt(16)
	s_nop 1
	v_mov_b64_e32 v[98:99], v[226:227]
	v_mov_b64_e32 v[100:101], v[228:229]
	v_mov_b64_e32 v[130:131], v[230:231]
	v_mov_b64_e32 v[132:133], v[232:233]
	global_load_dwordx4 v[218:221], v[238:239], off
	global_load_dwordx4 v[222:225], v[238:239], off offset:64
	global_load_dwordx4 v[226:229], v[238:239], off offset:256
	global_load_dwordx4 v[230:233], v[238:239], off offset:320
	s_and_b64 vcc, exec, s[6:7]
	v_lshlrev_b32_e32 v124, 16, v98
	v_and_b32_e32 v125, 0xffff0000, v98
	v_lshlrev_b32_e32 v98, 16, v99
	v_and_b32_e32 v99, 0xffff0000, v99
	v_pk_fma_f32 v[92:93], v[92:93], v[138:139], v[98:99]
	v_lshlrev_b32_e32 v98, 16, v131
	v_and_b32_e32 v99, 0xffff0000, v131
	v_pk_fma_f32 v[96:97], v[96:97], v[140:141], v[98:99]
	v_lshlrev_b32_e32 v98, 16, v100
	v_and_b32_e32 v99, 0xffff0000, v100
	v_pk_fma_f32 v[82:83], v[82:83], v[142:143], v[98:99]
	v_lshlrev_b32_e32 v98, 16, v132
	v_and_b32_e32 v99, 0xffff0000, v132
	v_pk_fma_f32 v[86:87], v[86:87], v[144:145], v[98:99]
	v_lshlrev_b32_e32 v98, 16, v101
	v_and_b32_e32 v99, 0xffff0000, v101
	v_pk_fma_f32 v[90:91], v[90:91], v[134:135], v[124:125]
	v_lshlrev_b32_e32 v124, 16, v130
	v_and_b32_e32 v125, 0xffff0000, v130
	v_pk_fma_f32 v[84:85], v[84:85], v[146:147], v[98:99]
	v_lshlrev_b32_e32 v98, 16, v133
	v_and_b32_e32 v99, 0xffff0000, v133
	v_pk_fma_f32 v[94:95], v[94:95], v[136:137], v[124:125]
	v_pk_fma_f32 v[88:89], v[88:89], v[148:149], v[98:99]
	global_store_dwordx4 v[120:121], v[90:93], off offset:512
	global_store_dwordx4 v[120:121], v[94:97], off offset:640
	global_store_dwordx4 v[120:121], v[82:85], off offset:528
	global_store_dwordx4 v[120:121], v[86:89], off offset:656
	s_cbranch_vccnz .LBB0_131
	v_cvt_pk_bf16_f32 v98, v90, v91
	v_cvt_pk_bf16_f32 v99, v92, v93
	v_cvt_pk_bf16_f32 v100, v82, v83
	v_cvt_pk_bf16_f32 v101, v84, v85
	global_store_dwordx4 v[118:119], v[98:101], off offset:256
	s_nop 1
	v_cvt_pk_bf16_f32 v98, v94, v95
	v_cvt_pk_bf16_f32 v99, v96, v97
	v_cvt_pk_bf16_f32 v100, v86, v87
	v_cvt_pk_bf16_f32 v101, v88, v89
	global_store_dwordx4 v[118:119], v[98:101], off offset:320

; template <bool XBF, bool WF32>
; DI void resid_epilogue(const float* __restrict__ xs, const bf16_t* __restrict__ xsb, float* __restrict__ out, bf16_t* __restrict__ xbn, float* __restrict__ ssq,
;                        const f32x4 (&acc)[2][2][4][2], int m0, int n0, int nt, bool wxb = true) {
;     ...
;     for (int bj = 0; bj < 2; ++bj)
; #pragma unroll
;         for (int nn = 0; nn < 2; ++nn) {
;             const size_t tok = (size_t)m0 + bj * 128 + wc * 32 + nn * 16 + fr;
;             float ss = 0.f;
; #pragma unroll
;             for (int ai = 0; ai < 2; ++ai) {
;                 float lo[8], hi[8];
;                 grp16(acc, ai, bj, nn, 1.f, lo, hi);
;                 const size_t o = tok * 1024 + n0 + ai * 128 + wr * 64 + 8 * fq;
;                 if (XBF) {
;                     const u32x4 xl = *(const u32x4*)(xsb + o), xh = *(const u32x4*)(xsb + o + 32);
; #pragma unroll
;                     for (int j = 0; j < 4; ++j) { lo[2 * j] += bf_lo(xl[j]); lo[2 * j + 1] += bf_hi(xl[j]); hi[2 * j] += bf_lo(xh[j]); hi[2 * j + 1] += bf_hi(xh[j]); }
;                 } else {
; #pragma unroll
;                     for (int q4 = 0; q4 < 2; ++q4) {
;                         const f32x4 xl = *(const f32x4*)(xs + o + 4 * q4), xh = *(const f32x4*)(xs + o + 32 + 4 * q4);
; #pragma unroll
;                         for (int j = 0; j < 4; ++j) { lo[4 * q4 + j] += xl[j]; hi[4 * q4 + j] += xh[j]; }
;                     }
;                 }
; #pragma unroll
;                 for (int i = 0; i < 8; ++i) ss += lo[i] * lo[i] + hi[i] * hi[i];
;                 if (WF32) {
; #pragma unroll
;                     for (int q4 = 0; q4 < 2; ++q4) {
;                         *(f32x4*)(out + o + 4 * q4) = (f32x4){lo[4 * q4], lo[4 * q4 + 1], lo[4 * q4 + 2], lo[4 * q4 + 3]};
;                         *(f32x4*)(out + o + 32 + 4 * q4) = (f32x4){hi[4 * q4], hi[4 * q4 + 1], hi[4 * q4 + 2], hi[4 * q4 + 3]};
;                     }
;                 }
; DI void ple_gate_apply(const Params& P, f32x4 (&acc)[2][2][4][2], int tile) {
;     ...
;                 const u32x4 gq = *ple_slot(P, tile, ai * 4 + bj * 2 + nn);
; #pragma unroll
;                 for (int e = 0; e < 8; ++e) {
;                     acc[ai][bj][e >> 2][nn][e & 3] *= dq8(gq[e >> 2], e & 3);
;                     acc[ai][bj][2 + (e >> 2)][nn][e & 3] *= dq8(gq[2 + (e >> 2)], e & 3);
;                 }
.LBB0_133:
	s_or_b64 exec, exec, s[20:21]
	s_waitcnt lgkmcnt(0)
	v_cvt_f32_ubyte1_e32 v83, v78
	v_cvt_f32_ubyte0_e32 v82, v78
	v_pk_mul_f32 v[94:95], v[82:83], s[84:85] op_sel_hi:[1,0]
	v_cvt_f32_ubyte1_e32 v83, v80
	v_cvt_f32_ubyte0_e32 v82, v80
	v_pk_mul_f32 v[96:97], v[82:83], s[84:85] op_sel_hi:[1,0]
	v_cvt_f32_ubyte3_e32 v83, v78
	v_cvt_f32_ubyte2_e32 v82, v78
	v_pk_mul_f32 v[98:99], v[82:83], s[84:85] op_sel_hi:[1,0]
	v_cvt_f32_ubyte3_e32 v83, v80
	v_cvt_f32_ubyte2_e32 v82, v80
	v_pk_mul_f32 v[100:101], v[82:83], s[84:85] op_sel_hi:[1,0]
	v_cvt_f32_ubyte1_e32 v83, v79
	v_cvt_f32_ubyte0_e32 v82, v79
	v_pk_mul_f32 v[102:103], v[82:83], s[84:85] op_sel_hi:[1,0]
	v_cvt_f32_ubyte1_e32 v83, v81
	v_cvt_f32_ubyte0_e32 v82, v81
	v_pk_mul_f32 v[104:105], v[82:83], s[84:85] op_sel_hi:[1,0]
	v_cvt_f32_ubyte3_e32 v83, v79
	v_cvt_f32_ubyte2_e32 v82, v79
	v_cvt_f32_ubyte3_e32 v79, v81
	v_cvt_f32_ubyte2_e32 v78, v81
	v_pk_mul_f32 v[80:81], v[78:79], s[84:85] op_sel_hi:[1,0]
	v_pk_mul_f32 v[106:107], v[82:83], s[84:85] op_sel_hi:[1,0]
	v_or_b32_e32 v84, 0x80, v184
	v_lshlrev_b32_e32 v0, 10, v84
	v_lshl_add_u64 v[78:79], v[0:1], 0, v[164:165]
	v_lshl_add_u64 v[82:83], v[78:79], 1, s[10:11]
	s_waitcnt vmcnt(18)
	s_nop 1
	v_mov_b64_e32 v[86:87], v[202:203]
	v_mov_b64_e32 v[88:89], v[204:205]
	v_mov_b64_e32 v[90:91], v[206:207]
	v_mov_b64_e32 v[92:93], v[208:209]
	s_and_b64 vcc, exec, s[6:7]
	v_lshlrev_b32_e32 v108, 16, v86
	v_and_b32_e32 v109, 0xffff0000, v86
	v_lshlrev_b32_e32 v86, 16, v87
	v_and_b32_e32 v87, 0xffff0000, v87
	v_pk_fma_f32 v[72:73], v[72:73], v[98:99], v[86:87]
	v_lshlrev_b32_e32 v86, 16, v91
	v_and_b32_e32 v87, 0xffff0000, v91
	v_pk_fma_f32 v[76:77], v[76:77], v[100:101], v[86:87]
	v_lshlrev_b32_e32 v86, 16, v88
	v_and_b32_e32 v87, 0xffff0000, v88
	v_pk_fma_f32 v[62:63], v[62:63], v[102:103], v[86:87]
	v_lshlrev_b32_e32 v86, 16, v92
	v_and_b32_e32 v87, 0xffff0000, v92
	v_pk_fma_f32 v[66:67], v[66:67], v[104:105], v[86:87]
	v_lshlrev_b32_e32 v86, 16, v89
	v_and_b32_e32 v87, 0xffff0000, v89
	v_pk_fma_f32 v[70:71], v[70:71], v[94:95], v[108:109]
	v_lshlrev_b32_e32 v94, 16, v90
	v_and_b32_e32 v95, 0xffff0000, v90
	v_pk_fma_f32 v[64:65], v[64:65], v[106:107], v[86:87]
	v_lshlrev_b32_e32 v86, 16, v93
	v_and_b32_e32 v87, 0xffff0000, v93
	v_pk_fma_f32 v[74:75], v[74:75], v[96:97], v[94:95]
	v_pk_fma_f32 v[68:69], v[68:69], v[80:81], v[86:87]
	v_lshl_add_u64 v[80:81], v[78:79], 2, s[60:61]
	v_lshl_add_u64 v[78:79], v[78:79], 1, s[12:13]
	global_store_dwordx4 v[80:81], v[70:73], off
	global_store_dwordx4 v[80:81], v[74:77], off offset:128
	global_store_dwordx4 v[80:81], v[62:65], off offset:16
	global_store_dwordx4 v[80:81], v[66:69], off offset:144
	s_cbranch_vccnz .LBB0_135
	v_cvt_pk_bf16_f32 v86, v70, v71
	v_cvt_pk_bf16_f32 v87, v72, v73
	v_cvt_pk_bf16_f32 v88, v62, v63
	v_cvt_pk_bf16_f32 v89, v64, v65
	global_store_dwordx4 v[78:79], v[86:89], off
	s_nop 1
	v_cvt_pk_bf16_f32 v86, v74, v75
	v_cvt_pk_bf16_f32 v87, v76, v77
	v_cvt_pk_bf16_f32 v88, v66, v67
	v_cvt_pk_bf16_f32 v89, v68, v69
	global_store_dwordx4 v[78:79], v[86:89], off offset:64
.LBB0_135:
	s_nop 1
	v_cvt_f32_ubyte1_e32 v87, v58
	v_cvt_f32_ubyte0_e32 v86, v58
	v_pk_mul_f32 v[90:91], v[86:87], s[84:85] op_sel_hi:[1,0]
	v_cvt_f32_ubyte1_e32 v87, v60
	v_cvt_f32_ubyte0_e32 v86, v60
	v_pk_mul_f32 v[92:93], v[86:87], s[84:85] op_sel_hi:[1,0]
	v_cvt_f32_ubyte3_e32 v87, v58
	v_cvt_f32_ubyte2_e32 v86, v58
	v_pk_mul_f32 v[94:95], v[86:87], s[84:85] op_sel_hi:[1,0]
	v_cvt_f32_ubyte3_e32 v87, v60
	v_cvt_f32_ubyte2_e32 v86, v60
	v_pk_mul_f32 v[96:97], v[86:87], s[84:85] op_sel_hi:[1,0]
	v_cvt_f32_ubyte1_e32 v87, v59
	v_cvt_f32_ubyte0_e32 v86, v59
	v_pk_mul_f32 v[98:99], v[86:87], s[84:85] op_sel_hi:[1,0]
	v_cvt_f32_ubyte1_e32 v87, v61
	v_cvt_f32_ubyte0_e32 v86, v61
	v_pk_mul_f32 v[100:101], v[86:87], s[84:85] op_sel_hi:[1,0]
	v_cvt_f32_ubyte3_e32 v87, v59
	v_cvt_f32_ubyte2_e32 v86, v59
	v_cvt_f32_ubyte3_e32 v59, v61
	v_cvt_f32_ubyte2_e32 v58, v61
	v_pk_mul_f32 v[102:103], v[86:87], s[84:85] op_sel_hi:[1,0]
	v_pk_mul_f32 v[104:105], v[58:59], s[84:85] op_sel_hi:[1,0]
	s_waitcnt vmcnt(20)
	s_nop 1
	v_mov_b64_e32 v[58:59], v[210:211]
	v_mov_b64_e32 v[60:61], v[212:213]
	v_mov_b64_e32 v[86:87], v[214:215]
	v_mov_b64_e32 v[88:89], v[216:217]
	s_and_b64 vcc, exec, s[6:7]
	v_lshlrev_b32_e32 v82, 16, v58
	v_and_b32_e32 v83, 0xffff0000, v58
	v_lshlrev_b32_e32 v58, 16, v59
	v_and_b32_e32 v59, 0xffff0000, v59
	v_pk_fma_f32 v[52:53], v[52:53], v[94:95], v[58:59]
	v_lshlrev_b32_e32 v58, 16, v87
	v_and_b32_e32 v59, 0xffff0000, v87
	v_pk_fma_f32 v[56:57], v[56:57], v[96:97], v[58:59]
	v_lshlrev_b32_e32 v58, 16, v60
	v_and_b32_e32 v59, 0xffff0000, v60
	v_pk_fma_f32 v[42:43], v[42:43], v[98:99], v[58:59]
	v_lshlrev_b32_e32 v58, 16, v88
	v_and_b32_e32 v59, 0xffff0000, v88
	v_pk_fma_f32 v[46:47], v[46:47], v[100:101], v[58:59]
	v_lshlrev_b32_e32 v58, 16, v61
	v_and_b32_e32 v59, 0xffff0000, v61
	v_pk_fma_f32 v[50:51], v[50:51], v[90:91], v[82:83]
	v_lshlrev_b32_e32 v82, 16, v86
	v_and_b32_e32 v83, 0xffff0000, v86
	v_pk_fma_f32 v[44:45], v[44:45], v[102:103], v[58:59]
	v_lshlrev_b32_e32 v58, 16, v89
	v_and_b32_e32 v59, 0xffff0000, v89
	v_pk_fma_f32 v[54:55], v[54:55], v[92:93], v[82:83]
	v_pk_fma_f32 v[48:49], v[48:49], v[104:105], v[58:59]
	global_store_dwordx4 v[80:81], v[50:53], off offset:512
	global_store_dwordx4 v[80:81], v[54:57], off offset:640
	global_store_dwordx4 v[80:81], v[42:45], off offset:528
	global_store_dwordx4 v[80:81], v[46:49], off offset:656
	s_cbranch_vccnz .LBB0_137
	v_cvt_pk_bf16_f32 v58, v50, v51
	v_cvt_pk_bf16_f32 v59, v52, v53
	v_cvt_pk_bf16_f32 v60, v42, v43
	v_cvt_pk_bf16_f32 v61, v44, v45
	global_store_dwordx4 v[78:79], v[58:61], off offset:256
	s_nop 1
	v_cvt_pk_bf16_f32 v58, v54, v55
	v_cvt_pk_bf16_f32 v59, v56, v57
	v_cvt_pk_bf16_f32 v60, v46, v47
	v_cvt_pk_bf16_f32 v61, v48, v49
	global_store_dwordx4 v[78:79], v[58:61], off offset:320

; template <bool XBF, bool WF32>
; DI void resid_epilogue(const float* __restrict__ xs, const bf16_t* __restrict__ xsb, float* __restrict__ out, bf16_t* __restrict__ xbn, float* __restrict__ ssq,
;                        const f32x4 (&acc)[2][2][4][2], int m0, int n0, int nt, bool wxb = true) {
;     ...
;     for (int bj = 0; bj < 2; ++bj)
; #pragma unroll
;         for (int nn = 0; nn < 2; ++nn) {
;             const size_t tok = (size_t)m0 + bj * 128 + wc * 32 + nn * 16 + fr;
;             float ss = 0.f;
; #pragma unroll
;             for (int ai = 0; ai < 2; ++ai) {
;                 float lo[8], hi[8];
;                 grp16(acc, ai, bj, nn, 1.f, lo, hi);
;                 const size_t o = tok * 1024 + n0 + ai * 128 + wr * 64 + 8 * fq;
;                 if (XBF) {
;                     const u32x4 xl = *(const u32x4*)(xsb + o), xh = *(const u32x4*)(xsb + o + 32);
; #pragma unroll
;                     for (int j = 0; j < 4; ++j) { lo[2 * j] += bf_lo(xl[j]); lo[2 * j + 1] += bf_hi(xl[j]); hi[2 * j] += bf_lo(xh[j]); hi[2 * j + 1] += bf_hi(xh[j]); }
;                 } else {
; #pragma unroll
;                     for (int q4 = 0; q4 < 2; ++q4) {
;                         const f32x4 xl = *(const f32x4*)(xs + o + 4 * q4), xh = *(const f32x4*)(xs + o + 32 + 4 * q4);
; #pragma unroll
;                         for (int j = 0; j < 4; ++j) { lo[4 * q4 + j] += xl[j]; hi[4 * q4 + j] += xh[j]; }
;                     }
;                 }
; #pragma unroll
;                 for (int i = 0; i < 8; ++i) ss += lo[i] * lo[i] + hi[i] * hi[i];
;                 if (WF32) {
; #pragma unroll
;                     for (int q4 = 0; q4 < 2; ++q4) {
;                         *(f32x4*)(out + o + 4 * q4) = (f32x4){lo[4 * q4], lo[4 * q4 + 1], lo[4 * q4 + 2], lo[4 * q4 + 3]};
;                         *(f32x4*)(out + o + 32 + 4 * q4) = (f32x4){hi[4 * q4], hi[4 * q4 + 1], hi[4 * q4 + 2], hi[4 * q4 + 3]};
;                     }
;                 }
; DI void ple_gate_apply(const Params& P, f32x4 (&acc)[2][2][4][2], int tile) {
;     ...
;                 const u32x4 gq = *ple_slot(P, tile, ai * 4 + bj * 2 + nn);
; #pragma unroll
;                 for (int e = 0; e < 8; ++e) {
;                     acc[ai][bj][e >> 2][nn][e & 3] *= dq8(gq[e >> 2], e & 3);
;                     acc[ai][bj][2 + (e >> 2)][nn][e & 3] *= dq8(gq[2 + (e >> 2)], e & 3);
;                 }
.LBB0_139:
	s_or_b64 exec, exec, s[20:21]
	s_waitcnt lgkmcnt(0)
	v_cvt_f32_ubyte1_e32 v43, v38
	v_cvt_f32_ubyte0_e32 v42, v38
	v_pk_mul_f32 v[54:55], v[42:43], s[84:85] op_sel_hi:[1,0]
	v_cvt_f32_ubyte1_e32 v43, v40
	v_cvt_f32_ubyte0_e32 v42, v40
	v_pk_mul_f32 v[56:57], v[42:43], s[84:85] op_sel_hi:[1,0]
	v_cvt_f32_ubyte3_e32 v43, v38
	v_cvt_f32_ubyte2_e32 v42, v38
	v_pk_mul_f32 v[58:59], v[42:43], s[84:85] op_sel_hi:[1,0]
	v_cvt_f32_ubyte3_e32 v43, v40
	v_cvt_f32_ubyte2_e32 v42, v40
	v_pk_mul_f32 v[60:61], v[42:43], s[84:85] op_sel_hi:[1,0]
	v_cvt_f32_ubyte1_e32 v43, v39
	v_cvt_f32_ubyte0_e32 v42, v39
	v_pk_mul_f32 v[62:63], v[42:43], s[84:85] op_sel_hi:[1,0]
	v_cvt_f32_ubyte1_e32 v43, v41
	v_cvt_f32_ubyte0_e32 v42, v41
	v_pk_mul_f32 v[64:65], v[42:43], s[84:85] op_sel_hi:[1,0]
	v_cvt_f32_ubyte3_e32 v43, v39
	v_cvt_f32_ubyte2_e32 v42, v39
	v_cvt_f32_ubyte3_e32 v39, v41
	v_cvt_f32_ubyte2_e32 v38, v41
	v_pk_mul_f32 v[40:41], v[38:39], s[84:85] op_sel_hi:[1,0]
	v_pk_mul_f32 v[66:67], v[42:43], s[84:85] op_sel_hi:[1,0]
	v_or_b32_e32 v44, 0x90, v184
	v_lshlrev_b32_e32 v0, 10, v44
	v_lshl_add_u64 v[38:39], v[0:1], 0, v[164:165]
	v_lshl_add_u64 v[42:43], v[38:39], 1, s[10:11]
	s_waitcnt vmcnt(14)
	s_nop 1
	v_mov_b64_e32 v[46:47], v[218:219]
	v_mov_b64_e32 v[48:49], v[220:221]
	v_mov_b64_e32 v[50:51], v[222:223]
	v_mov_b64_e32 v[52:53], v[224:225]
	s_and_b64 vcc, exec, s[6:7]
	v_lshlrev_b32_e32 v68, 16, v46
	v_and_b32_e32 v69, 0xffff0000, v46
	v_lshlrev_b32_e32 v46, 16, v47
	v_and_b32_e32 v47, 0xffff0000, v47
	v_pk_fma_f32 v[32:33], v[32:33], v[58:59], v[46:47]
	v_lshlrev_b32_e32 v46, 16, v51
	v_and_b32_e32 v47, 0xffff0000, v51
	v_pk_fma_f32 v[36:37], v[36:37], v[60:61], v[46:47]
	v_lshlrev_b32_e32 v46, 16, v48
	v_and_b32_e32 v47, 0xffff0000, v48
	v_pk_fma_f32 v[22:23], v[22:23], v[62:63], v[46:47]
	v_lshlrev_b32_e32 v46, 16, v52
	v_and_b32_e32 v47, 0xffff0000, v52
	v_pk_fma_f32 v[26:27], v[26:27], v[64:65], v[46:47]
	v_lshlrev_b32_e32 v46, 16, v49
	v_and_b32_e32 v47, 0xffff0000, v49
	v_pk_fma_f32 v[30:31], v[30:31], v[54:55], v[68:69]
	v_lshlrev_b32_e32 v54, 16, v50
	v_and_b32_e32 v55, 0xffff0000, v50
	v_pk_fma_f32 v[24:25], v[24:25], v[66:67], v[46:47]
	v_lshlrev_b32_e32 v46, 16, v53
	v_and_b32_e32 v47, 0xffff0000, v53
	v_pk_fma_f32 v[34:35], v[34:35], v[56:57], v[54:55]
	v_pk_fma_f32 v[28:29], v[28:29], v[40:41], v[46:47]
	v_lshl_add_u64 v[40:41], v[38:39], 2, s[60:61]
	v_lshl_add_u64 v[38:39], v[38:39], 1, s[12:13]
	global_store_dwordx4 v[40:41], v[30:33], off
	global_store_dwordx4 v[40:41], v[34:37], off offset:128
	global_store_dwordx4 v[40:41], v[22:25], off offset:16
	global_store_dwordx4 v[40:41], v[26:29], off offset:144
	s_cbranch_vccnz .LBB0_141
	v_cvt_pk_bf16_f32 v46, v30, v31
	v_cvt_pk_bf16_f32 v47, v32, v33
	v_cvt_pk_bf16_f32 v48, v22, v23
	v_cvt_pk_bf16_f32 v49, v24, v25
	global_store_dwordx4 v[38:39], v[46:49], off
	s_nop 1
	v_cvt_pk_bf16_f32 v46, v34, v35
	v_cvt_pk_bf16_f32 v47, v36, v37
	v_cvt_pk_bf16_f32 v48, v26, v27
	v_cvt_pk_bf16_f32 v49, v28, v29
	global_store_dwordx4 v[38:39], v[46:49], off offset:64
.LBB0_141:
	s_nop 1
	v_cvt_f32_ubyte1_e32 v47, v18
	v_cvt_f32_ubyte0_e32 v46, v18
	v_pk_mul_f32 v[50:51], v[46:47], s[84:85] op_sel_hi:[1,0]
	v_cvt_f32_ubyte1_e32 v47, v20
	v_cvt_f32_ubyte0_e32 v46, v20
	v_pk_mul_f32 v[52:53], v[46:47], s[84:85] op_sel_hi:[1,0]
	v_cvt_f32_ubyte3_e32 v47, v18
	v_cvt_f32_ubyte2_e32 v46, v18
	v_pk_mul_f32 v[54:55], v[46:47], s[84:85] op_sel_hi:[1,0]
	v_cvt_f32_ubyte3_e32 v47, v20
	v_cvt_f32_ubyte2_e32 v46, v20
	v_pk_mul_f32 v[56:57], v[46:47], s[84:85] op_sel_hi:[1,0]
	v_cvt_f32_ubyte1_e32 v47, v19
	v_cvt_f32_ubyte0_e32 v46, v19
	v_pk_mul_f32 v[58:59], v[46:47], s[84:85] op_sel_hi:[1,0]
	v_cvt_f32_ubyte1_e32 v47, v21
	v_cvt_f32_ubyte0_e32 v46, v21
	v_pk_mul_f32 v[60:61], v[46:47], s[84:85] op_sel_hi:[1,0]
	v_cvt_f32_ubyte3_e32 v47, v19
	v_cvt_f32_ubyte2_e32 v46, v19
	v_cvt_f32_ubyte3_e32 v19, v21
	v_cvt_f32_ubyte2_e32 v18, v21
	v_pk_mul_f32 v[62:63], v[46:47], s[84:85] op_sel_hi:[1,0]
	v_pk_mul_f32 v[64:65], v[18:19], s[84:85] op_sel_hi:[1,0]
	s_waitcnt vmcnt(16)
	s_nop 1
	v_mov_b64_e32 v[18:19], v[226:227]
	v_mov_b64_e32 v[20:21], v[228:229]
	v_mov_b64_e32 v[46:47], v[230:231]
	v_mov_b64_e32 v[48:49], v[232:233]
	s_and_b64 vcc, exec, s[6:7]
	v_lshlrev_b32_e32 v42, 16, v18
	v_and_b32_e32 v43, 0xffff0000, v18
	v_lshlrev_b32_e32 v18, 16, v19
	v_and_b32_e32 v19, 0xffff0000, v19
	v_pk_fma_f32 v[12:13], v[12:13], v[54:55], v[18:19]
	v_lshlrev_b32_e32 v18, 16, v47
	v_and_b32_e32 v19, 0xffff0000, v47
	v_pk_fma_f32 v[16:17], v[16:17], v[56:57], v[18:19]
	v_lshlrev_b32_e32 v18, 16, v20
	v_and_b32_e32 v19, 0xffff0000, v20
	v_pk_fma_f32 v[2:3], v[2:3], v[58:59], v[18:19]
	v_lshlrev_b32_e32 v18, 16, v48
	v_and_b32_e32 v19, 0xffff0000, v48
	v_pk_fma_f32 v[6:7], v[6:7], v[60:61], v[18:19]
	v_lshlrev_b32_e32 v18, 16, v21
	v_and_b32_e32 v19, 0xffff0000, v21
	v_pk_fma_f32 v[10:11], v[10:11], v[50:51], v[42:43]
	v_lshlrev_b32_e32 v42, 16, v46
	v_and_b32_e32 v43, 0xffff0000, v46
	v_pk_fma_f32 v[4:5], v[4:5], v[62:63], v[18:19]
	v_lshlrev_b32_e32 v18, 16, v49
	v_and_b32_e32 v19, 0xffff0000, v49
	v_pk_fma_f32 v[14:15], v[14:15], v[52:53], v[42:43]
	v_pk_fma_f32 v[8:9], v[8:9], v[64:65], v[18:19]
	global_store_dwordx4 v[40:41], v[10:13], off offset:512
	global_store_dwordx4 v[40:41], v[14:17], off offset:640
	global_store_dwordx4 v[40:41], v[2:5], off offset:528
	global_store_dwordx4 v[40:41], v[6:9], off offset:656
	s_cbranch_vccnz .LBB0_143
	v_cvt_pk_bf16_f32 v18, v10, v11
	v_cvt_pk_bf16_f32 v19, v12, v13
	v_cvt_pk_bf16_f32 v20, v2, v3
	v_cvt_pk_bf16_f32 v21, v4, v5
	global_store_dwordx4 v[38:39], v[18:21], off offset:256
	s_nop 1
	v_cvt_pk_bf16_f32 v18, v14, v15
	v_cvt_pk_bf16_f32 v19, v16, v17
	v_cvt_pk_bf16_f32 v20, v6, v7
	v_cvt_pk_bf16_f32 v21, v8, v9
	global_store_dwordx4 v[38:39], v[18:21], off offset:320
